# GEMM SP1 load segment: fragment ds_reads issued first, next-tile pointer arithmetic behind them (under LDS latency)
# speedup vs baseline: 1.0158x; 1.0158x over previous
; #define PG8_STAGE(bufoff, gbase, voff) do { _Pragma("unroll") for (int _i = 0; _i < 2; ++_i) \
;         __builtin_amdgcn_global_load_lds((const unsigned*)((const char*)(gbase) + (voff)[_i]), (PG8_LAS unsigned*)(lds + (bufoff) + ldsw + _i * 8192), 16, 0, 0); } while (0)
; #define PG8_LDA(dst, b, h) do { _Pragma("unroll") for (int m = 0; m < 4; ++m) _Pragma("unroll") for (int k = 0; k < 2; ++k) dst[m][k] = *(const PG8_LAS bf16x8*)(lds + PG8_SA(b, h) + aoff + m * 2048 + k * 1024); } while (0)
; #define PG8_LDB(dst, b, h) do { _Pragma("unroll") for (int n = 0; n < 2; ++n) _Pragma("unroll") for (int k = 0; k < 2; ++k) dst[n][k] = *(const PG8_LAS bf16x8*)(lds + PG8_SB(b, h) + boff + n * 2048 + k * 1024); } while (0)
; #define PG8_MMA(ai, bj, At, Bt) do { __builtin_amdgcn_s_setprio(1); _Pragma("unroll") for (int m = 0; m < 4; ++m) _Pragma("unroll") for (int n = 0; n < 2; ++n) _Pragma("unroll") for (int k = 0; k < 2; ++k) \
;         acc[ai][bj][m][n] = __builtin_amdgcn_mfma_f32_16x16x32_bf16(Bt[n][k], At[m][k], acc[ai][bj][m][n], 0, 0, 0); __builtin_amdgcn_s_setprio(0); } while (0)
; #define PG8_WAIT_V(n) asm volatile("s_waitcnt vmcnt(" #n ")" ::: "memory")
; #define PG8_WAIT_L(n) asm volatile("s_waitcnt lgkmcnt(" #n ")" ::: "memory")
; #define PG8_BAR __builtin_amdgcn_s_barrier()
; #define PG8_SCHED __builtin_amdgcn_sched_barrier(0)
; template <class Epi, class Sched, bool ALIGN_EPI = false, bool SP2 = false>
; __device__ __forceinline__ void gemm_phase(PG8_LAS unsigned char* lds, const Gemm g, const Sched& S, const Epi& E, const int tid_in) {
;     ...
;             PG8_LDB(B0, 0, 0); PG8_LDB(B1, 0, 1); PG8_SCHED; PG8_LDA(At, 0, 0); PG8_STAGE(PG8_SA(1, 1), a1 + hstep, voffA);
;             PG8_WAIT_V(8); PG8_WAIT_L(0); PG8_BAR; PG8_MMA(0, 0, At, B0); PG8_MMA(0, 1, At, B1); PG8_BAR; PG8_SCHED;
.LBB0_115:
	ds_read_b128 v[134:137], v248
	ds_read_b128 v[138:141], v248 offset:1024
	ds_read_b128 v[142:145], v248 offset:2048
	ds_read_b128 v[146:149], v248 offset:3072
	ds_read_b128 v[150:153], v249
	ds_read_b128 v[154:157], v249 offset:1024
	ds_read_b128 v[158:161], v249 offset:2048
	ds_read_b128 v[180:183], v249 offset:3072
	ds_read_b128 v[184:187], v179
	ds_read_b128 v[188:191], v179 offset:1024
	ds_read_b128 v[192:195], v179 offset:2048
	ds_read_b128 v[196:199], v179 offset:3072
	ds_read_b128 v[200:203], v179 offset:4096
	ds_read_b128 v[204:207], v179 offset:5120
	ds_read_b128 v[208:211], v179 offset:6144
	ds_read_b128 v[212:215], v179 offset:7168
	s_add_i32 m0, s60, 0xc000
	s_add_i32 s77, s52, 2
	s_add_u32 vcc_lo, s2, s10
	s_addc_u32 s53, s3, s11
	s_add_u32 s44, s50, s10
	s_addc_u32 s45, s51, s11
	s_cmp_eq_u32 s68, s52
	s_cselect_b32 s53, s49, s53
	s_cselect_b32 s52, s48, vcc_lo
	s_cselect_b32 vcc_hi, s43, s45
	s_cselect_b32 vcc_lo, s42, s44
	s_add_i32 s16, 0, 0x10000
	s_add_i32 s17, 0, 0x14000
	global_load_lds_dwordx4 v132, s[2:3]
	s_add_i32 m0, s60, 0xe000
	s_nop 0
	global_load_lds_dwordx4 v130, s[2:3]
	s_waitcnt vmcnt(8)
	s_waitcnt lgkmcnt(0)
	s_barrier
	s_setprio 1
	s_waitcnt lgkmcnt(0)
	v_mfma_f32_16x16x32_bf16 v[126:129], v[134:137], v[184:187], v[126:129]
	v_mfma_f32_16x16x32_bf16 v[122:125], v[142:145], v[184:187], v[122:125]
	v_mfma_f32_16x16x32_bf16 v[110:113], v[134:137], v[192:195], v[110:113]
	v_mfma_f32_16x16x32_bf16 v[106:109], v[142:145], v[192:195], v[106:109]
	v_mfma_f32_16x16x32_bf16 v[94:97], v[134:137], v[200:203], v[94:97]
	v_mfma_f32_16x16x32_bf16 v[90:93], v[142:145], v[200:203], v[90:93]
	v_mfma_f32_16x16x32_bf16 v[78:81], v[134:137], v[208:211], v[78:81]
	v_mfma_f32_16x16x32_bf16 v[74:77], v[142:145], v[208:211], v[74:77]
	v_mfma_f32_16x16x32_bf16 v[126:129], v[138:141], v[188:191], v[126:129]
	v_mfma_f32_16x16x32_bf16 v[122:125], v[146:149], v[188:191], v[122:125]
	v_mfma_f32_16x16x32_bf16 v[110:113], v[138:141], v[196:199], v[110:113]
	v_mfma_f32_16x16x32_bf16 v[106:109], v[146:149], v[196:199], v[106:109]
	v_mfma_f32_16x16x32_bf16 v[94:97], v[138:141], v[204:207], v[94:97]
	v_mfma_f32_16x16x32_bf16 v[90:93], v[146:149], v[204:207], v[90:93]
	v_mfma_f32_16x16x32_bf16 v[78:81], v[138:141], v[212:215], v[78:81]
	v_mfma_f32_16x16x32_bf16 v[74:77], v[146:149], v[212:215], v[74:77]
	s_setprio 0
	s_setprio 1
	v_mfma_f32_16x16x32_bf16 v[118:121], v[150:153], v[184:187], v[118:121]
	v_mfma_f32_16x16x32_bf16 v[114:117], v[158:161], v[184:187], v[114:117]
	v_mfma_f32_16x16x32_bf16 v[102:105], v[150:153], v[192:195], v[102:105]
	v_mfma_f32_16x16x32_bf16 v[98:101], v[158:161], v[192:195], v[98:101]
	v_mfma_f32_16x16x32_bf16 v[86:89], v[150:153], v[200:203], v[86:89]
	v_mfma_f32_16x16x32_bf16 v[82:85], v[158:161], v[200:203], v[82:85]
	v_mfma_f32_16x16x32_bf16 v[70:73], v[150:153], v[208:211], v[70:73]
	v_mfma_f32_16x16x32_bf16 v[66:69], v[158:161], v[208:211], v[66:69]
	v_mfma_f32_16x16x32_bf16 v[118:121], v[154:157], v[188:191], v[118:121]
	v_mfma_f32_16x16x32_bf16 v[114:117], v[180:183], v[188:191], v[114:117]
	v_mfma_f32_16x16x32_bf16 v[102:105], v[154:157], v[196:199], v[102:105]
	v_mfma_f32_16x16x32_bf16 v[98:101], v[180:183], v[196:199], v[98:101]
	v_mfma_f32_16x16x32_bf16 v[86:89], v[154:157], v[204:207], v[86:89]
	v_mfma_f32_16x16x32_bf16 v[82:85], v[180:183], v[204:207], v[82:85]
	v_mfma_f32_16x16x32_bf16 v[70:73], v[154:157], v[212:215], v[70:73]
	v_mfma_f32_16x16x32_bf16 v[66:69], v[180:183], v[212:215], v[66:69]
	s_setprio 0
	s_barrier
	s_add_i32 s16, s16, s59
	s_add_u32 s98, vcc_lo, 0x80
	s_addc_u32 s99, vcc_hi, 0
	s_add_u32 s100, s52, 0x80
	s_addc_u32 s101, s53, 0
	s_mov_b32 m0, s16
	ds_read_b128 v[184:187], v179 offset:16384
	ds_read_b128 v[188:191], v179 offset:17408
	ds_read_b128 v[192:195], v179 offset:18432
	ds_read_b128 v[196:199], v179 offset:19456
	ds_read_b128 v[200:203], v179 offset:20480
	ds_read_b128 v[204:207], v179 offset:21504
	ds_read_b128 v[208:211], v179 offset:22528
	ds_read_b128 v[212:215], v179 offset:23552
	global_load_lds_dwordx4 v164, vcc
	s_add_i32 m0, s16, 0x2000
	s_add_i32 s16, s17, s59
	global_load_lds_dwordx4 v168, vcc
	s_add_u32 vcc_lo, vcc_lo, s82
	s_addc_u32 vcc_hi, vcc_hi, 0
	s_mov_b32 m0, s16
	s_nop 0
	global_load_lds_dwordx4 v164, vcc
	s_add_i32 m0, s16, 0x2000
	s_nop 0
	global_load_lds_dwordx4 v168, vcc
	s_mov_b32 m0, s60
	s_nop 0
	global_load_lds_dwordx4 v162, s[52:53]
	s_mov_b32 m0, s61
	s_nop 0
	global_load_lds_dwordx4 v166, s[52:53]
	s_waitcnt vmcnt(8)
	s_waitcnt lgkmcnt(0)
	s_barrier
; #define PG8_STAGE(bufoff, gbase, voff) do { _Pragma("unroll") for (int _i = 0; _i < 2; ++_i) \
;         __builtin_amdgcn_global_load_lds((const unsigned*)((const char*)(gbase) + (voff)[_i]), (PG8_LAS unsigned*)(lds + (bufoff) + ldsw + _i * 8192), 16, 0, 0); } while (0)
; #define PG8_LDA(dst, b, h) do { _Pragma("unroll") for (int m = 0; m < 4; ++m) _Pragma("unroll") for (int k = 0; k < 2; ++k) dst[m][k] = *(const PG8_LAS bf16x8*)(lds + PG8_SA(b, h) + aoff + m * 2048 + k * 1024); } while (0)
; #define PG8_LDB(dst, b, h) do { _Pragma("unroll") for (int n = 0; n < 2; ++n) _Pragma("unroll") for (int k = 0; k < 2; ++k) dst[n][k] = *(const PG8_LAS bf16x8*)(lds + PG8_SB(b, h) + boff + n * 2048 + k * 1024); } while (0)
; #define PG8_MMA(ai, bj, At, Bt) do { __builtin_amdgcn_s_setprio(1); _Pragma("unroll") for (int m = 0; m < 4; ++m) _Pragma("unroll") for (int n = 0; n < 2; ++n) _Pragma("unroll") for (int k = 0; k < 2; ++k) \
;         acc[ai][bj][m][n] = __builtin_amdgcn_mfma_f32_16x16x32_bf16(Bt[n][k], At[m][k], acc[ai][bj][m][n], 0, 0, 0); __builtin_amdgcn_s_setprio(0); } while (0)
; #define PG8_WAIT_V(n) asm volatile("s_waitcnt vmcnt(" #n ")" ::: "memory")
; #define PG8_WAIT_L(n) asm volatile("s_waitcnt lgkmcnt(" #n ")" ::: "memory")
; #define PG8_BAR __builtin_amdgcn_s_barrier()
; #define PG8_SCHED __builtin_amdgcn_sched_barrier(0)
; template <class Epi, class Sched, bool ALIGN_EPI = false, bool SP2 = false>
; __device__ __forceinline__ void gemm_phase(PG8_LAS unsigned char* lds, const Gemm g, const Sched& S, const Epi& E, const int tid_in) {
;     ...
;             PG8_WAIT_V(8); PG8_WAIT_L(0); PG8_BAR; PG8_MMA(0, 0, At, B0); PG8_MMA(0, 1, At, B1); PG8_BAR; PG8_SCHED;
;             PG8_LDA(At, 0, 1); PG8_STAGE(PG8_SB(0, 0), b2, voffB); PG8_STAGE(PG8_SB(0, 1), b2 + hstep, voffB); PG8_STAGE(PG8_SA(0, 0), a2, voffA);
;             PG8_WAIT_V(8); PG8_WAIT_L(0); PG8_BAR; PG8_MMA(1, 0, At, B0); PG8_MMA(1, 1, At, B1); PG8_BAR; PG8_SCHED;
;             PG8_LDB(B0, 1, 0); PG8_LDB(B1, 1, 1); PG8_SCHED; PG8_LDA(At, 1, 0); PG8_STAGE(PG8_SA(0, 1), a2 + hstep, voffA);
;             PG8_WAIT_V(8); PG8_WAIT_L(0); PG8_BAR; PG8_MMA(0, 0, At, B0); PG8_MMA(0, 1, At, B1); PG8_BAR; PG8_SCHED;
	s_setprio 1
	s_waitcnt lgkmcnt(0)
	v_mfma_f32_16x16x32_bf16 v[62:65], v[134:137], v[184:187], v[62:65]
	v_mfma_f32_16x16x32_bf16 v[58:61], v[142:145], v[184:187], v[58:61]
	v_mfma_f32_16x16x32_bf16 v[46:49], v[134:137], v[192:195], v[46:49]
	v_mfma_f32_16x16x32_bf16 v[42:45], v[142:145], v[192:195], v[42:45]
	v_mfma_f32_16x16x32_bf16 v[30:33], v[134:137], v[200:203], v[30:33]
	v_mfma_f32_16x16x32_bf16 v[26:29], v[142:145], v[200:203], v[26:29]
	v_mfma_f32_16x16x32_bf16 v[14:17], v[134:137], v[208:211], v[14:17]
	v_mfma_f32_16x16x32_bf16 v[10:13], v[142:145], v[208:211], v[10:13]
	v_mfma_f32_16x16x32_bf16 v[62:65], v[138:141], v[188:191], v[62:65]
	v_mfma_f32_16x16x32_bf16 v[58:61], v[146:149], v[188:191], v[58:61]
	v_mfma_f32_16x16x32_bf16 v[46:49], v[138:141], v[196:199], v[46:49]
	v_mfma_f32_16x16x32_bf16 v[42:45], v[146:149], v[196:199], v[42:45]
	v_mfma_f32_16x16x32_bf16 v[30:33], v[138:141], v[204:207], v[30:33]
	v_mfma_f32_16x16x32_bf16 v[26:29], v[146:149], v[204:207], v[26:29]
	v_mfma_f32_16x16x32_bf16 v[14:17], v[138:141], v[212:215], v[14:17]
	v_mfma_f32_16x16x32_bf16 v[10:13], v[146:149], v[212:215], v[10:13]
	s_setprio 0
	s_setprio 1
	v_mfma_f32_16x16x32_bf16 v[54:57], v[150:153], v[184:187], v[54:57]
	v_mfma_f32_16x16x32_bf16 v[50:53], v[158:161], v[184:187], v[50:53]
	v_mfma_f32_16x16x32_bf16 v[38:41], v[150:153], v[192:195], v[38:41]
	v_mfma_f32_16x16x32_bf16 v[34:37], v[158:161], v[192:195], v[34:37]
	v_mfma_f32_16x16x32_bf16 v[22:25], v[150:153], v[200:203], v[22:25]
	v_mfma_f32_16x16x32_bf16 v[18:21], v[158:161], v[200:203], v[18:21]
	v_mfma_f32_16x16x32_bf16 v[6:9], v[150:153], v[208:211], v[6:9]
	v_mfma_f32_16x16x32_bf16 v[2:5], v[158:161], v[208:211], v[2:5]
	v_mfma_f32_16x16x32_bf16 v[54:57], v[154:157], v[188:191], v[54:57]
	v_mfma_f32_16x16x32_bf16 v[50:53], v[180:183], v[188:191], v[50:53]
	v_mfma_f32_16x16x32_bf16 v[38:41], v[154:157], v[196:199], v[38:41]
	v_mfma_f32_16x16x32_bf16 v[34:37], v[180:183], v[196:199], v[34:37]
	v_mfma_f32_16x16x32_bf16 v[22:25], v[154:157], v[204:207], v[22:25]
	v_mfma_f32_16x16x32_bf16 v[18:21], v[180:183], v[204:207], v[18:21]
	v_mfma_f32_16x16x32_bf16 v[6:9], v[154:157], v[212:215], v[6:9]
	v_mfma_f32_16x16x32_bf16 v[2:5], v[180:183], v[212:215], v[2:5]
	s_setprio 0
	s_barrier
	s_add_i32 s16, 0, 0x18000
	s_add_i32 s17, 0, 0x1c000
	ds_read_b128 v[134:137], v250
	ds_read_b128 v[138:141], v250 offset:1024
	ds_read_b128 v[142:145], v250 offset:2048
	ds_read_b128 v[146:149], v250 offset:3072
	ds_read_b128 v[150:153], v251
	ds_read_b128 v[154:157], v251 offset:1024
	ds_read_b128 v[158:161], v251 offset:2048
	ds_read_b128 v[180:183], v251 offset:3072
	s_add_u32 s52, s52, s82
	s_addc_u32 s53, s53, 0
	s_mov_b32 m0, s62
	ds_read_b128 v[184:187], v179 offset:32768
	ds_read_b128 v[188:191], v179 offset:33792
	ds_read_b128 v[192:195], v179 offset:34816
	ds_read_b128 v[196:199], v179 offset:35840
	ds_read_b128 v[200:203], v179 offset:36864
	ds_read_b128 v[204:207], v179 offset:37888
	ds_read_b128 v[208:211], v179 offset:38912
	ds_read_b128 v[212:215], v179 offset:39936
	global_load_lds_dwordx4 v162, s[52:53]
	s_mov_b32 m0, s63
	s_nop 0
	global_load_lds_dwordx4 v166, s[52:53]
	s_waitcnt vmcnt(8)
	s_waitcnt lgkmcnt(0)
	s_barrier
	s_setprio 1
	s_waitcnt lgkmcnt(0)
	v_mfma_f32_16x16x32_bf16 v[126:129], v[134:137], v[184:187], v[126:129]
	v_mfma_f32_16x16x32_bf16 v[122:125], v[142:145], v[184:187], v[122:125]
	v_mfma_f32_16x16x32_bf16 v[110:113], v[134:137], v[192:195], v[110:113]
	v_mfma_f32_16x16x32_bf16 v[106:109], v[142:145], v[192:195], v[106:109]
	v_mfma_f32_16x16x32_bf16 v[94:97], v[134:137], v[200:203], v[94:97]
	v_mfma_f32_16x16x32_bf16 v[90:93], v[142:145], v[200:203], v[90:93]
	v_mfma_f32_16x16x32_bf16 v[78:81], v[134:137], v[208:211], v[78:81]
	v_mfma_f32_16x16x32_bf16 v[74:77], v[142:145], v[208:211], v[74:77]
	v_mfma_f32_16x16x32_bf16 v[126:129], v[138:141], v[188:191], v[126:129]
	v_mfma_f32_16x16x32_bf16 v[122:125], v[146:149], v[188:191], v[122:125]
	v_mfma_f32_16x16x32_bf16 v[110:113], v[138:141], v[196:199], v[110:113]
	v_mfma_f32_16x16x32_bf16 v[106:109], v[146:149], v[196:199], v[106:109]
	v_mfma_f32_16x16x32_bf16 v[94:97], v[138:141], v[204:207], v[94:97]
	v_mfma_f32_16x16x32_bf16 v[90:93], v[146:149], v[204:207], v[90:93]
	v_mfma_f32_16x16x32_bf16 v[78:81], v[138:141], v[212:215], v[78:81]
	v_mfma_f32_16x16x32_bf16 v[74:77], v[146:149], v[212:215], v[74:77]
	s_setprio 0
	s_setprio 1
	v_mfma_f32_16x16x32_bf16 v[118:121], v[150:153], v[184:187], v[118:121]
	v_mfma_f32_16x16x32_bf16 v[114:117], v[158:161], v[184:187], v[114:117]
	v_mfma_f32_16x16x32_bf16 v[102:105], v[150:153], v[192:195], v[102:105]
	v_mfma_f32_16x16x32_bf16 v[98:101], v[158:161], v[192:195], v[98:101]
	v_mfma_f32_16x16x32_bf16 v[86:89], v[150:153], v[200:203], v[86:89]
	v_mfma_f32_16x16x32_bf16 v[82:85], v[158:161], v[200:203], v[82:85]
	v_mfma_f32_16x16x32_bf16 v[70:73], v[150:153], v[208:211], v[70:73]
	v_mfma_f32_16x16x32_bf16 v[66:69], v[158:161], v[208:211], v[66:69]
	v_mfma_f32_16x16x32_bf16 v[118:121], v[154:157], v[188:191], v[118:121]
	v_mfma_f32_16x16x32_bf16 v[114:117], v[180:183], v[188:191], v[114:117]
	v_mfma_f32_16x16x32_bf16 v[102:105], v[154:157], v[196:199], v[102:105]
	v_mfma_f32_16x16x32_bf16 v[98:101], v[180:183], v[196:199], v[98:101]
	v_mfma_f32_16x16x32_bf16 v[86:89], v[154:157], v[204:207], v[86:89]
	v_mfma_f32_16x16x32_bf16 v[82:85], v[180:183], v[204:207], v[82:85]
	v_mfma_f32_16x16x32_bf16 v[70:73], v[154:157], v[212:215], v[70:73]
	v_mfma_f32_16x16x32_bf16 v[66:69], v[180:183], v[212:215], v[66:69]
	s_setprio 0
	s_barrier
; #define PG8_STAGE(bufoff, gbase, voff) do { _Pragma("unroll") for (int _i = 0; _i < 2; ++_i) \
;         __builtin_amdgcn_global_load_lds((const unsigned*)((const char*)(gbase) + (voff)[_i]), (PG8_LAS unsigned*)(lds + (bufoff) + ldsw + _i * 8192), 16, 0, 0); } while (0)
; #define PG8_LDA(dst, b, h) do { _Pragma("unroll") for (int m = 0; m < 4; ++m) _Pragma("unroll") for (int k = 0; k < 2; ++k) dst[m][k] = *(const PG8_LAS bf16x8*)(lds + PG8_SA(b, h) + aoff + m * 2048 + k * 1024); } while (0)
; #define PG8_MMA(ai, bj, At, Bt) do { __builtin_amdgcn_s_setprio(1); _Pragma("unroll") for (int m = 0; m < 4; ++m) _Pragma("unroll") for (int n = 0; n < 2; ++n) _Pragma("unroll") for (int k = 0; k < 2; ++k) \
;         acc[ai][bj][m][n] = __builtin_amdgcn_mfma_f32_16x16x32_bf16(Bt[n][k], At[m][k], acc[ai][bj][m][n], 0, 0, 0); __builtin_amdgcn_s_setprio(0); } while (0)
; #define PG8_WAIT_V(n) asm volatile("s_waitcnt vmcnt(" #n ")" ::: "memory")
; #define PG8_WAIT_L(n) asm volatile("s_waitcnt lgkmcnt(" #n ")" ::: "memory")
; #define PG8_BAR __builtin_amdgcn_s_barrier()
; #define PG8_SCHED __builtin_amdgcn_sched_barrier(0)
; template <class Epi, class Sched, bool ALIGN_EPI = false, bool SP2 = false>
; __device__ __forceinline__ void gemm_phase(PG8_LAS unsigned char* lds, const Gemm g, const Sched& S, const Epi& E, const int tid_in) {
;     ...
;         for (int t = 0; t < nt; t += 2) {
;             const bool last = (t == nt - 2);
;     ...
;             PG8_LDA(At, 1, 1); PG8_STAGE(PG8_SB(1, 0), b3, voffB); PG8_STAGE(PG8_SB(1, 1), b3 + hstep, voffB); PG8_STAGE(PG8_SA(1, 0), a3, voffA);
;             PG8_WAIT_V(8); PG8_WAIT_L(0); PG8_BAR; PG8_MMA(1, 0, At, B0); PG8_MMA(1, 1, At, B1); PG8_BAR; PG8_SCHED;
	s_add_i32 s16, s16, s59
	s_mov_b32 m0, s16
	ds_read_b128 v[184:187], v179 offset:49152
	ds_read_b128 v[188:191], v179 offset:50176
	ds_read_b128 v[192:195], v179 offset:51200
	ds_read_b128 v[196:199], v179 offset:52224
	ds_read_b128 v[200:203], v179 offset:53248
	ds_read_b128 v[204:207], v179 offset:54272
	ds_read_b128 v[208:211], v179 offset:55296
	ds_read_b128 v[212:215], v179 offset:56320
	global_load_lds_dwordx4 v164, s[98:99]
	s_add_i32 m0, s16, 0x2000
	s_add_i32 s16, s17, s59
	global_load_lds_dwordx4 v168, s[98:99]
	s_add_u32 vcc_lo, vcc_lo, 0x80
	s_addc_u32 vcc_hi, vcc_hi, 0
	s_mov_b32 m0, s16
	s_nop 0
	global_load_lds_dwordx4 v164, vcc
	s_add_i32 m0, s16, 0x2000
	s_nop 0
	global_load_lds_dwordx4 v168, vcc
	s_mov_b32 m0, s66
	s_nop 0
	global_load_lds_dwordx4 v162, s[100:101]
	s_mov_b32 m0, s67
	s_nop 0
	global_load_lds_dwordx4 v166, s[100:101]
	s_waitcnt vmcnt(8)
	s_waitcnt lgkmcnt(0)
	s_barrier
	s_setprio 1
	s_waitcnt lgkmcnt(0)
	v_mfma_f32_16x16x32_bf16 v[62:65], v[134:137], v[184:187], v[62:65]
	v_mfma_f32_16x16x32_bf16 v[58:61], v[142:145], v[184:187], v[58:61]
	v_mfma_f32_16x16x32_bf16 v[46:49], v[134:137], v[192:195], v[46:49]
	v_mfma_f32_16x16x32_bf16 v[42:45], v[142:145], v[192:195], v[42:45]
	v_mfma_f32_16x16x32_bf16 v[30:33], v[134:137], v[200:203], v[30:33]
	v_mfma_f32_16x16x32_bf16 v[26:29], v[142:145], v[200:203], v[26:29]
	v_mfma_f32_16x16x32_bf16 v[14:17], v[134:137], v[208:211], v[14:17]
	v_mfma_f32_16x16x32_bf16 v[10:13], v[142:145], v[208:211], v[10:13]
	v_mfma_f32_16x16x32_bf16 v[62:65], v[138:141], v[188:191], v[62:65]
	v_mfma_f32_16x16x32_bf16 v[58:61], v[146:149], v[188:191], v[58:61]
	v_mfma_f32_16x16x32_bf16 v[46:49], v[138:141], v[196:199], v[46:49]
	v_mfma_f32_16x16x32_bf16 v[42:45], v[146:149], v[196:199], v[42:45]
	v_mfma_f32_16x16x32_bf16 v[30:33], v[138:141], v[204:207], v[30:33]
	v_mfma_f32_16x16x32_bf16 v[26:29], v[146:149], v[204:207], v[26:29]
	v_mfma_f32_16x16x32_bf16 v[14:17], v[138:141], v[212:215], v[14:17]
	v_mfma_f32_16x16x32_bf16 v[10:13], v[146:149], v[212:215], v[10:13]
	s_setprio 0
	s_setprio 1
	v_mfma_f32_16x16x32_bf16 v[54:57], v[150:153], v[184:187], v[54:57]
	v_mfma_f32_16x16x32_bf16 v[50:53], v[158:161], v[184:187], v[50:53]
	v_mfma_f32_16x16x32_bf16 v[38:41], v[150:153], v[192:195], v[38:41]
	v_mfma_f32_16x16x32_bf16 v[34:37], v[158:161], v[192:195], v[34:37]
	v_mfma_f32_16x16x32_bf16 v[22:25], v[150:153], v[200:203], v[22:25]
	v_mfma_f32_16x16x32_bf16 v[18:21], v[158:161], v[200:203], v[18:21]
	v_mfma_f32_16x16x32_bf16 v[6:9], v[150:153], v[208:211], v[6:9]
	v_mfma_f32_16x16x32_bf16 v[2:5], v[158:161], v[208:211], v[2:5]
	v_mfma_f32_16x16x32_bf16 v[54:57], v[154:157], v[188:191], v[54:57]
	v_mfma_f32_16x16x32_bf16 v[50:53], v[180:183], v[188:191], v[50:53]
	v_mfma_f32_16x16x32_bf16 v[38:41], v[154:157], v[196:199], v[38:41]
	v_mfma_f32_16x16x32_bf16 v[34:37], v[180:183], v[196:199], v[34:37]
	v_mfma_f32_16x16x32_bf16 v[22:25], v[154:157], v[204:207], v[22:25]
	v_mfma_f32_16x16x32_bf16 v[18:21], v[180:183], v[204:207], v[18:21]
	v_mfma_f32_16x16x32_bf16 v[6:9], v[154:157], v[212:215], v[6:9]
	v_mfma_f32_16x16x32_bf16 v[2:5], v[180:183], v[212:215], v[2:5]
	s_setprio 0
	s_barrier
	s_add_u32 s10, s10, 0x100
	s_addc_u32 s11, s11, 0
	v_lshl_add_u64 v[132:133], v[132:133], 0, s[88:89]
	v_lshl_add_u64 v[130:131], v[130:131], 0, s[88:89]
	s_cmp_ge_u32 s77, s65
	s_mov_b32 s52, s77
	s_cbranch_scc0 .LBB0_115
	s_and_b64 vcc, exec, s[46:47]
	s_cbranch_vccz .LBB0_118
	s_barrier
